# PIN3: per-loop placement pin: 4-byte pad before the GEMM2 unit loop only (GEMM2 K-loop at the baseline's 8-byte phase, all other loops as in the final)
# baseline (speedup 1.0000x reference)
; #define PG8_BAR __builtin_amdgcn_s_barrier()
; template <class Epi, bool SPLITA>
; __device__ __forceinline__ void gemm_phase(LAS unsigned char* lds, const Gemm g, const StaticOrder& S, const Epi& E) {
;     ...
;         if (!has_next) break;
; #pragma unroll
;         for (int a = 0; a < 2; ++a)
; #pragma unroll
;             for (int b = 0; b < 2; ++b)
; #pragma unroll
;                 for (int m = 0; m < 4; ++m)
; #pragma unroll
;                     for (int n = 0; n < 2; ++n) acc[a][b][m][n] = (f32x4){0.f, 0.f, 0.f, 0.f};
;         cur = nxt; cB = nB; ++ui;
;         if (wr == 1) PG8_BAR;
.LBB0_479:
	s_andn2_b64 vcc, exec, s[0:1]
	s_mov_b32 s94, s70
	s_mov_b32 s0, s93
	s_mov_b64 s[76:77], s[74:75]
	s_cbranch_vccz .LBB0_507
	s_nop 0
